# NSA cmp-branch K/V tile staging: 8 serialized load/wait/ds_write per tile re-issued as one batch with counted waits
# speedup vs baseline: 1.0316x; 1.0060x over previous
.LBB0_793:
	s_lshl_b64 s[0:1], s[16:17], 14
	v_lshlrev_b32_e32 v2, 4, v206
	v_ashrrev_i32_e32 v4, 3, v206
	s_add_u32 s0, s8, s0
	s_addc_u32 s1, s9, s1
	v_and_b32_e32 v32, 0x70, v2
	v_lshl_add_u32 v2, v4, 7, v32
	s_add_u32 s100, s0, 0x2000
	s_addc_u32 s101, s1, 0
	v_add_u32_e32 v3, 0x1000, v2
	global_load_dwordx4 v[128:131], v2, s[0:1]
	global_load_dwordx4 v[132:135], v3, s[0:1]
	global_load_dwordx4 v[136:139], v2, s[100:101]
	global_load_dwordx4 v[140:143], v3, s[100:101]
	s_movk_i32 s11, 0x90
	v_mad_u32_u24 v8, v4, s11, v32
	s_mov_b64 s[14:15], s[16:17]
	s_mov_b32 s13, 0
	v_xor_b32_e32 v1, 32, v214
	s_lshl_b32 s0, s16, 7
	s_sub_i32 s11, 0, s0
	s_mov_b64 s[0:1], -1
	s_mov_b32 s16, 0xf149f2ca
	v_and_b32_e32 v2, 64, v214
	v_add_u32_e32 v74, 64, v2
	s_waitcnt lgkmcnt(0)
	s_barrier
	s_waitcnt vmcnt(3)
	ds_write_b128 v8, v[128:131]
	s_waitcnt vmcnt(2)
	ds_write_b128 v8, v[132:135] offset:4608
	s_waitcnt vmcnt(1)
	ds_write_b128 v8, v[136:139] offset:9216
	s_waitcnt vmcnt(0)
	ds_write_b128 v8, v[140:143] offset:13824
	v_cmp_lt_i32_e32 vcc, v1, v74
	s_waitcnt lgkmcnt(0)
	s_barrier
	v_cndmask_b32_e32 v1, v214, v1, vcc
	v_lshlrev_b32_e32 v165, 2, v1

.LBB0_798:
	s_lshl_b64 s[0:1], s[16:17], 14
	v_lshlrev_b32_e32 v32, 4, v206
	v_ashrrev_i32_e32 v36, 3, v206
	s_add_u32 s0, s8, s0
	s_addc_u32 s1, s9, s1
	v_and_b32_e32 v40, 0x70, v32
	v_lshl_add_u32 v34, v36, 7, v40
	s_add_u32 s100, s0, 0x2000
	s_addc_u32 s101, s1, 0
	v_add_u32_e32 v35, 0x1000, v34
	global_load_dwordx4 v[128:131], v34, s[0:1]
	global_load_dwordx4 v[132:135], v35, s[0:1]
	global_load_dwordx4 v[136:139], v34, s[100:101]
	global_load_dwordx4 v[140:143], v35, s[100:101]
	s_lshl_b64 s[0:1], s[16:17], 8
	s_add_u32 s0, s11, s0
	s_addc_u32 s1, s13, s1
	v_and_b32_e32 v37, 0xf0, v32
	v_ashrrev_i32_e32 v38, 4, v206
	v_lshl_add_u32 v39, v38, 10, v37
	s_add_u32 s100, s0, 0x8000
	s_addc_u32 s101, s1, 0
	v_add_u32_e32 v42, 0x4000, v39
	global_load_dwordx4 v[144:147], v39, s[0:1]
	global_load_dwordx4 v[148:151], v42, s[0:1]
	global_load_dwordx4 v[152:155], v39, s[100:101]
	global_load_dwordx4 v[156:159], v42, s[100:101]
	s_movk_i32 s6, 0x90
	v_mad_u32_u24 v40, v36, s6, v40
	s_movk_i32 s6, 0x108
	v_mad_u32_u24 v41, v38, s6, v37
	v_add_u32_e32 v41, 0x4800, v41
	v_add_u32_e32 v34, 0x1080, v41
	v_add_u32_e32 v35, 0x2100, v41
	v_add_u32_e32 v36, 0x3180, v41
	v_writelane_b32 v251, s16, 29
	v_writelane_b32 v251, s17, 30
	s_lshl_b32 s14, s16, 7
	s_movk_i32 s30, 0x90
	s_barrier
	s_waitcnt vmcnt(7)
	ds_write_b128 v40, v[128:131]
	s_waitcnt vmcnt(6)
	ds_write_b128 v40, v[132:135] offset:4608
	s_waitcnt vmcnt(5)
	ds_write_b128 v40, v[136:139] offset:9216
	s_waitcnt vmcnt(4)
	ds_write_b128 v40, v[140:143] offset:13824
	s_waitcnt vmcnt(3)
	ds_write2_b64 v41, v[144:145], v[146:147] offset1:1
	s_waitcnt vmcnt(2)
	ds_write2_b64 v34, v[148:149], v[150:151] offset1:1
	s_waitcnt vmcnt(1)
	ds_write2_b64 v35, v[152:153], v[154:155] offset1:1
	s_waitcnt vmcnt(0)
	ds_write2_b64 v36, v[156:157], v[158:159] offset1:1
	s_mov_b64 s[6:7], -1
	s_movk_i32 s1, 0x4800
	s_mov_b32 s0, 0
	s_waitcnt lgkmcnt(0)
	s_barrier
	s_branch .LBB0_800
